# add: P8 down-proj epilogue with 16 H loads in flight (rolling), P9 norm gain hoisted out of the row loop, P4 conservative vmcnt(0) dropped
# speedup vs baseline: 1.0109x; 1.0052x over previous
.LBB0_884:
	s_lshl_b64 s[16:17], s[0:1], 10
	s_and_b64 vcc, exec, s[18:19]
	s_cbranch_vccz .LBB0_878
	s_mul_i32 s18, s0, 0xfe03f81
	s_add_i32 s18, s18, 0xfe03f0
	v_alignbit_b32 v42, s18, s18, 4
	v_cmp_gt_u32_e32 vcc, s30, v42
	s_cbranch_vccz .LBB0_877
	v_mov_b32_e32 v11, 0
	v_mov_b32_e32 v10, v11
	v_mov_b32_e32 v9, v11
	v_mov_b32_e32 v8, v11
	s_branch .LBB0_878

.LBB0_1464:
	v_lshl_add_u32 v146, s43, 8, v155
	v_lshl_or_b32 v144, s44, 8, v157
	v_ashrrev_i32_e32 v145, 31, v144
	v_lshlrev_b64 v[144:145], 2, v[144:145]
	s_mov_b64 s[20:21], -1
	s_and_b64 vcc, exec, s[4:5]
	v_mov_b32_e32 v162, v146
	v_ashrrev_i32_e32 v163, 31, v162
	v_lshlrev_b64 v[162:163], 13, v[162:163]
	v_lshl_add_u64 v[162:163], s[8:9], 0, v[162:163]
	v_lshl_add_u64 v[162:163], v[162:163], 0, v[144:145]
	v_or_b32_e32 v164, 16, v146
	v_ashrrev_i32_e32 v165, 31, v164
	v_lshlrev_b64 v[164:165], 13, v[164:165]
	v_lshl_add_u64 v[164:165], s[8:9], 0, v[164:165]
	v_lshl_add_u64 v[164:165], v[164:165], 0, v[144:145]
	v_or_b32_e32 v166, 32, v146
	v_ashrrev_i32_e32 v167, 31, v166
	v_lshlrev_b64 v[166:167], 13, v[166:167]
	v_lshl_add_u64 v[166:167], s[8:9], 0, v[166:167]
	v_lshl_add_u64 v[166:167], v[166:167], 0, v[144:145]
	v_or_b32_e32 v168, 48, v146
	v_ashrrev_i32_e32 v169, 31, v168
	v_lshlrev_b64 v[168:169], 13, v[168:169]
	v_lshl_add_u64 v[168:169], s[8:9], 0, v[168:169]
	v_lshl_add_u64 v[168:169], v[168:169], 0, v[144:145]
	v_add_u32_e32 v170, 0x80, v146
	v_ashrrev_i32_e32 v171, 31, v170
	v_lshlrev_b64 v[170:171], 13, v[170:171]
	v_lshl_add_u64 v[170:171], s[8:9], 0, v[170:171]
	v_lshl_add_u64 v[170:171], v[170:171], 0, v[144:145]
	v_add_u32_e32 v172, 0x90, v146
	v_ashrrev_i32_e32 v173, 31, v172
	v_lshlrev_b64 v[172:173], 13, v[172:173]
	v_lshl_add_u64 v[172:173], s[8:9], 0, v[172:173]
	v_lshl_add_u64 v[172:173], v[172:173], 0, v[144:145]
	v_add_u32_e32 v174, 0xa0, v146
	v_ashrrev_i32_e32 v175, 31, v174
	v_lshlrev_b64 v[174:175], 13, v[174:175]
	v_lshl_add_u64 v[174:175], s[8:9], 0, v[174:175]
	v_lshl_add_u64 v[174:175], v[174:175], 0, v[144:145]
	v_add_u32_e32 v176, 0xb0, v146
	v_ashrrev_i32_e32 v177, 31, v176
	v_lshlrev_b64 v[176:177], 13, v[176:177]
	v_lshl_add_u64 v[176:177], s[8:9], 0, v[176:177]
	v_lshl_add_u64 v[176:177], v[176:177], 0, v[144:145]
	global_load_dwordx4 v[184:187], v[162:163], off offset:16
	global_load_dwordx4 v[180:183], v[162:163], off
	global_load_dwordx4 v[192:195], v[162:163], off offset:528
	global_load_dwordx4 v[188:191], v[162:163], off offset:512
	global_load_dwordx4 v[200:203], v[164:165], off offset:16
	global_load_dwordx4 v[196:199], v[164:165], off
	global_load_dwordx4 v[212:215], v[164:165], off offset:528
	global_load_dwordx4 v[204:207], v[164:165], off offset:512
	global_load_dwordx4 v[220:223], v[166:167], off offset:16
	global_load_dwordx4 v[216:219], v[166:167], off
	global_load_dwordx4 v[228:231], v[166:167], off offset:528
	global_load_dwordx4 v[224:227], v[166:167], off offset:512
	global_load_dwordx4 v[236:239], v[168:169], off offset:16
	global_load_dwordx4 v[232:235], v[168:169], off
	global_load_dwordx4 v[144:147], v[168:169], off offset:528
	global_load_dwordx4 v[240:243], v[168:169], off offset:512
	s_waitcnt vmcnt(12)
	v_pk_add_f32 v[124:125], v[124:125], v[180:181]
	v_pk_add_f32 v[126:127], v[126:127], v[182:183]
	v_pk_add_f32 v[120:121], v[120:121], v[184:185]
	v_pk_add_f32 v[122:123], v[122:123], v[186:187]
	v_pk_add_f32 v[116:117], v[116:117], v[188:189]
	v_pk_add_f32 v[118:119], v[118:119], v[190:191]
	v_pk_add_f32 v[112:113], v[112:113], v[192:193]
	v_pk_add_f32 v[114:115], v[114:115], v[194:195]
	global_store_dwordx4 v[162:163], v[124:127], off
	global_store_dwordx4 v[162:163], v[120:123], off offset:16
	global_store_dwordx4 v[162:163], v[116:119], off offset:512
	global_store_dwordx4 v[162:163], v[112:115], off offset:528
	global_load_dwordx4 v[184:187], v[170:171], off offset:16
	global_load_dwordx4 v[180:183], v[170:171], off
	global_load_dwordx4 v[192:195], v[170:171], off offset:528
	global_load_dwordx4 v[188:191], v[170:171], off offset:512
	s_waitcnt vmcnt(16)
	v_pk_add_f32 v[108:109], v[108:109], v[196:197]
	v_pk_add_f32 v[110:111], v[110:111], v[198:199]
	v_pk_add_f32 v[104:105], v[104:105], v[200:201]
	v_pk_add_f32 v[106:107], v[106:107], v[202:203]
	v_pk_add_f32 v[100:101], v[100:101], v[204:205]
	v_pk_add_f32 v[102:103], v[102:103], v[206:207]
	v_pk_add_f32 v[96:97], v[96:97], v[212:213]
	v_pk_add_f32 v[98:99], v[98:99], v[214:215]
	global_store_dwordx4 v[164:165], v[108:111], off
	global_store_dwordx4 v[164:165], v[104:107], off offset:16
	global_store_dwordx4 v[164:165], v[100:103], off offset:512
	global_store_dwordx4 v[164:165], v[96:99], off offset:528
	global_load_dwordx4 v[200:203], v[172:173], off offset:16
	global_load_dwordx4 v[196:199], v[172:173], off
	global_load_dwordx4 v[212:215], v[172:173], off offset:528
	global_load_dwordx4 v[204:207], v[172:173], off offset:512
	s_waitcnt vmcnt(20)
	v_pk_add_f32 v[92:93], v[92:93], v[216:217]
	v_pk_add_f32 v[94:95], v[94:95], v[218:219]
	v_pk_add_f32 v[88:89], v[88:89], v[220:221]
	v_pk_add_f32 v[90:91], v[90:91], v[222:223]
	v_pk_add_f32 v[84:85], v[84:85], v[224:225]
	v_pk_add_f32 v[86:87], v[86:87], v[226:227]
	v_pk_add_f32 v[80:81], v[80:81], v[228:229]
	v_pk_add_f32 v[82:83], v[82:83], v[230:231]
	global_store_dwordx4 v[166:167], v[92:95], off
	global_store_dwordx4 v[166:167], v[88:91], off offset:16
	global_store_dwordx4 v[166:167], v[84:87], off offset:512
	global_store_dwordx4 v[166:167], v[80:83], off offset:528
	global_load_dwordx4 v[220:223], v[174:175], off offset:16
	global_load_dwordx4 v[216:219], v[174:175], off
	global_load_dwordx4 v[228:231], v[174:175], off offset:528
	global_load_dwordx4 v[224:227], v[174:175], off offset:512
	s_waitcnt vmcnt(24)
	v_pk_add_f32 v[76:77], v[76:77], v[232:233]
	v_pk_add_f32 v[78:79], v[78:79], v[234:235]
	v_pk_add_f32 v[72:73], v[72:73], v[236:237]
	v_pk_add_f32 v[74:75], v[74:75], v[238:239]
	v_pk_add_f32 v[68:69], v[68:69], v[240:241]
	v_pk_add_f32 v[70:71], v[70:71], v[242:243]
	v_pk_add_f32 v[64:65], v[64:65], v[144:145]
	v_pk_add_f32 v[66:67], v[66:67], v[146:147]
	global_store_dwordx4 v[168:169], v[76:79], off
	global_store_dwordx4 v[168:169], v[72:75], off offset:16
	global_store_dwordx4 v[168:169], v[68:71], off offset:512
	global_store_dwordx4 v[168:169], v[64:67], off offset:528
	global_load_dwordx4 v[236:239], v[176:177], off offset:16
	global_load_dwordx4 v[232:235], v[176:177], off
	global_load_dwordx4 v[144:147], v[176:177], off offset:528
	global_load_dwordx4 v[240:243], v[176:177], off offset:512
	s_waitcnt vmcnt(24)
	v_pk_add_f32 v[60:61], v[60:61], v[180:181]
	v_pk_add_f32 v[62:63], v[62:63], v[182:183]
	v_pk_add_f32 v[56:57], v[56:57], v[184:185]
	v_pk_add_f32 v[58:59], v[58:59], v[186:187]
	v_pk_add_f32 v[52:53], v[52:53], v[188:189]
	v_pk_add_f32 v[54:55], v[54:55], v[190:191]
	v_pk_add_f32 v[48:49], v[48:49], v[192:193]
	v_pk_add_f32 v[50:51], v[50:51], v[194:195]
	global_store_dwordx4 v[170:171], v[60:63], off
	global_store_dwordx4 v[170:171], v[56:59], off offset:16
	global_store_dwordx4 v[170:171], v[52:55], off offset:512
	global_store_dwordx4 v[170:171], v[48:51], off offset:528
	s_waitcnt vmcnt(20)
	v_pk_add_f32 v[44:45], v[44:45], v[196:197]
	v_pk_add_f32 v[46:47], v[46:47], v[198:199]
	v_pk_add_f32 v[40:41], v[40:41], v[200:201]
	v_pk_add_f32 v[42:43], v[42:43], v[202:203]
	v_pk_add_f32 v[36:37], v[36:37], v[204:205]
	v_pk_add_f32 v[38:39], v[38:39], v[206:207]
	v_pk_add_f32 v[32:33], v[32:33], v[212:213]
	v_pk_add_f32 v[34:35], v[34:35], v[214:215]
	global_store_dwordx4 v[172:173], v[44:47], off
	global_store_dwordx4 v[172:173], v[40:43], off offset:16
	global_store_dwordx4 v[172:173], v[36:39], off offset:512
	global_store_dwordx4 v[172:173], v[32:35], off offset:528
	s_waitcnt vmcnt(16)
	v_pk_add_f32 v[28:29], v[28:29], v[216:217]
	v_pk_add_f32 v[30:31], v[30:31], v[218:219]
	v_pk_add_f32 v[24:25], v[24:25], v[220:221]
	v_pk_add_f32 v[26:27], v[26:27], v[222:223]
	v_pk_add_f32 v[20:21], v[20:21], v[224:225]
	v_pk_add_f32 v[22:23], v[22:23], v[226:227]
	v_pk_add_f32 v[16:17], v[16:17], v[228:229]
	v_pk_add_f32 v[18:19], v[18:19], v[230:231]
	global_store_dwordx4 v[174:175], v[28:31], off
	global_store_dwordx4 v[174:175], v[24:27], off offset:16
	global_store_dwordx4 v[174:175], v[20:23], off offset:512
	global_store_dwordx4 v[174:175], v[16:19], off offset:528
	s_waitcnt vmcnt(12)
	v_pk_add_f32 v[12:13], v[12:13], v[232:233]
	v_pk_add_f32 v[14:15], v[14:15], v[234:235]
	v_pk_add_f32 v[8:9], v[8:9], v[236:237]
	v_pk_add_f32 v[10:11], v[10:11], v[238:239]
	v_pk_add_f32 v[4:5], v[4:5], v[240:241]
	v_pk_add_f32 v[6:7], v[6:7], v[242:243]
	v_pk_add_f32 v[0:1], v[0:1], v[144:145]
	v_pk_add_f32 v[2:3], v[2:3], v[146:147]
	global_store_dwordx4 v[176:177], v[12:15], off
	global_store_dwordx4 v[176:177], v[8:11], off offset:16
	global_store_dwordx4 v[176:177], v[4:7], off offset:512
	global_store_dwordx4 v[176:177], v[0:3], off offset:528
	s_cbranch_vccnz .LBB0_1453
	s_andn2_b64 vcc, exec, s[12:13]
	s_cbranch_vccnz .LBB0_1452
	s_barrier
	s_branch .LBB0_1452

.LBB0_1598:
	s_cmp_lt_i32 s80, 10
	s_cselect_b64 s[2:3], -1, 0
	s_and_b64 s[0:1], s[2:3], s[0:1]
	s_andn2_b64 vcc, exec, s[0:1]
	s_cbranch_vccnz .LBB0_1608
	s_lshl_b32 s0, s88, 3
	s_add_i32 s12, s84, s0
	s_cmpk_gt_i32 s12, 0x223f
	s_cbranch_scc1 .LBB0_1608
	v_readlane_b32 s16, v245, 0
	v_readlane_b32 s18, v245, 2
	v_readlane_b32 s19, v245, 3
	s_add_u32 s13, s18, 0x4000000
	s_addc_u32 s14, s19, 0
	s_lshl_b32 s4, s33, 3
	s_ashr_i32 s1, s0, 31
	s_add_u32 s0, s84, s0
	s_addc_u32 s1, 0, s1
	s_lshl_b64 s[0:1], s[0:1], 13
	v_readlane_b32 s17, v245, 1
	s_waitcnt vmcnt(0)
	v_mov_b32_e32 v17, 0
	v_lshlrev_b32_e32 v16, 4, v179
	s_add_u32 s0, s96, s0
	v_lshlrev_b32_e32 v0, 2, v179
	v_lshl_add_u64 v[18:19], s[16:17], 0, v[16:17]
	s_mov_b64 s[6:7], 0x1000
	s_addc_u32 s1, s97, s1
	v_lshl_add_u64 v[20:21], v[18:19], 0, s[6:7]
	s_mov_b64 s[6:7], 0x1400
	v_lshl_add_u64 v[2:3], s[0:1], 0, v[16:17]
	v_lshlrev_b32_e32 v16, 2, v0
	v_mbcnt_lo_u32_b32 v0, -1, 0
	v_lshl_add_u64 v[22:23], v[18:19], 0, s[6:7]
	s_mov_b64 s[6:7], 0x1800
	v_mbcnt_hi_u32_b32 v32, -1, v0
	v_lshl_add_u64 v[24:25], v[18:19], 0, s[6:7]
	s_mov_b64 s[6:7], 0x1c00
	s_mov_b64 s[0:1], 0x2f01c00
	s_ashr_i32 s5, s4, 31
	v_and_b32_e32 v0, 64, v32
	s_mov_b32 s3, 0
	v_lshl_add_u64 v[26:27], v[18:19], 0, s[6:7]
	v_lshl_add_u64 v[28:29], v[2:3], 0, s[0:1]
	s_lshl_b64 s[6:7], s[4:5], 13
	v_mov_b32_e32 v30, 0x358637bd
	s_mov_b32 s5, 0xf800000
	v_mov_b32_e32 v31, 0x260
	s_movk_i32 s15, 0x1000
	v_add_u32_e32 v33, 64, v0
	v_xor_b32_e32 v34, 1, v32
	v_xor_b32_e32 v35, 2, v32
	v_xor_b32_e32 v36, 4, v32
	v_xor_b32_e32 v37, 8, v32
	v_xor_b32_e32 v38, 16, v32
	v_xor_b32_e32 v39, 32, v32
	global_load_dwordx4 v[96:99], v[18:19], off
	global_load_dwordx4 v[100:103], v[18:19], off offset:1024
	global_load_dwordx4 v[104:107], v[18:19], off offset:2048
	global_load_dwordx4 v[108:111], v[18:19], off offset:3072
	global_load_dwordx4 v[112:115], v[20:21], off
	global_load_dwordx4 v[116:119], v[22:23], off
	global_load_dwordx4 v[120:123], v[24:25], off
	global_load_dwordx4 v[124:127], v[26:27], off
	s_branch .LBB0_1602

.LBB0_1606:
	s_andn2_b64 vcc, exec, s[0:1]
	s_cbranch_vccnz .LBB0_1601
	global_load_dwordx4 v[0:3], v[28:29], off offset:-3072
	global_load_dwordx4 v[8:11], v[28:29], off offset:-2048
	global_load_dwordx4 v[4:7], v[28:29], off
	global_load_dwordx4 v[12:15], v[28:29], off offset:-1024
	v_add_co_u32_e32 v56, vcc, 0xfffff000, v28
	s_waitcnt vmcnt(3)
	v_mul_f32_e32 v84, v0, v0
	v_addc_co_u32_e32 v57, vcc, -1, v29, vcc
	global_load_dwordx4 v[40:43], v[56:57], off offset:-3072
	global_load_dwordx4 v[44:47], v[56:57], off offset:-2048
	global_load_dwordx4 v[48:51], v[56:57], off offset:-1024
	global_load_dwordx4 v[52:55], v[28:29], off offset:-4096
	v_cmp_lt_i32_e32 vcc, v34, v33
	s_waitcnt vmcnt(6)
	v_pk_mul_f32 v[62:63], v[8:9], v[8:9]
	v_cndmask_b32_e32 v60, v32, v34, vcc
	v_lshlrev_b32_e32 v83, 2, v60
	v_pk_mul_f32 v[60:61], v[10:11], v[10:11]
	s_waitcnt vmcnt(4)
	v_mul_f32_e32 v64, v13, v13
	v_mul_f32_e32 v66, v15, v15
	v_mul_f32_e32 v81, v6, v6
	v_mul_f32_e32 v90, v7, v7
	v_pk_mov_b32 v[68:69], v[62:63], v[60:61] op_sel:[1,0]
	v_mov_b32_e32 v63, v61
	v_pk_fma_f32 v[60:61], v[12:13], v[12:13], v[64:65] op_sel_hi:[1,1,0]
	v_pk_fma_f32 v[64:65], v[14:15], v[14:15], v[66:67] op_sel_hi:[1,1,0]
	v_pk_add_f32 v[62:63], v[68:69], v[62:63]
	v_mov_b32_e32 v61, v81
	v_mov_b32_e32 v65, v90
	v_pk_add_f32 v[60:61], v[60:61], v[64:65]
	v_mul_f32_e32 v85, v1, v1
	v_mul_f32_e32 v86, v2, v2
	v_mul_f32_e32 v87, v3, v3
	v_mul_f32_e32 v88, v4, v4
	v_mul_f32_e32 v89, v5, v5
	v_pk_add_f32 v[62:63], v[62:63], v[62:63] op_sel:[0,1] op_sel_hi:[1,0]
	v_cmp_lt_i32_e32 vcc, v35, v33
	v_mov_b32_e32 v63, v89
	s_waitcnt vmcnt(3)
	v_mov_b32_e32 v70, v41
	s_waitcnt vmcnt(2)
	v_mov_b32_e32 v71, v45
	v_mov_b32_e32 v74, v43
	v_mov_b32_e32 v75, v47
	v_mov_b32_e32 v66, v40
	v_mov_b32_e32 v67, v44
	v_mov_b32_e32 v72, v42
	v_mov_b32_e32 v73, v46
	s_waitcnt vmcnt(1)
	v_pk_mul_f32 v[76:77], v[50:51], v[50:51]
	v_pk_mul_f32 v[78:79], v[48:49], v[48:49]
	v_pk_mul_f32 v[68:69], v[70:71], v[70:71]
	v_pk_mul_f32 v[70:71], v[74:75], v[74:75]
	v_pk_mov_b32 v[74:75], v[78:79], v[76:77] op_sel:[1,0]
	v_mov_b32_e32 v79, v77
	v_pk_fma_f32 v[64:65], v[66:67], v[66:67], v[68:69]
	v_pk_fma_f32 v[66:67], v[72:73], v[72:73], v[70:71]
	s_waitcnt vmcnt(0)
	v_mul_f32_e32 v80, v53, v53
	v_mul_f32_e32 v82, v55, v55
	v_pk_add_f32 v[68:69], v[74:75], v[78:79]
	v_pk_add_f32 v[64:65], v[64:65], v[66:67]
	v_pk_fma_f32 v[76:77], v[52:53], v[52:53], v[80:81] op_sel_hi:[1,1,0]
	v_pk_fma_f32 v[80:81], v[54:55], v[54:55], v[82:83] op_sel_hi:[1,1,0]
	v_pk_add_f32 v[66:67], v[68:69], v[68:69] op_sel:[0,1] op_sel_hi:[1,0]
	v_pk_add_f32 v[64:65], v[64:65], v[64:65] op_sel:[0,1] op_sel_hi:[1,0]
	v_mov_b32_e32 v77, v86
	v_mov_b32_e32 v81, v87
	v_mov_b32_e32 v67, v85
	v_mov_b32_e32 v65, v84
	v_pk_add_f32 v[68:69], v[76:77], v[80:81]
	v_pk_add_f32 v[64:65], v[64:65], v[66:67]
	s_nop 0
	v_pk_add_f32 v[64:65], v[64:65], v[68:69]
	s_nop 0
	v_pk_add_f32 v[64:65], v[64:65], v[64:65] op_sel:[0,1] op_sel_hi:[1,0]
	s_nop 0
	v_mov_b32_e32 v65, v88
	v_pk_add_f32 v[62:63], v[64:65], v[62:63]
	s_nop 0
	v_pk_add_f32 v[60:61], v[62:63], v[60:61]
	v_cndmask_b32_e32 v62, v32, v35, vcc
	v_add_f32_e32 v60, v60, v61
	ds_bpermute_b32 v61, v83, v60
	v_lshlrev_b32_e32 v62, 2, v62
	v_cmp_lt_i32_e32 vcc, v36, v33
	s_waitcnt lgkmcnt(0)
	v_add_f32_e32 v60, v60, v61
	ds_bpermute_b32 v61, v62, v60
	v_cndmask_b32_e32 v62, v32, v36, vcc
	v_lshlrev_b32_e32 v62, 2, v62
	v_cmp_lt_i32_e32 vcc, v37, v33
	s_waitcnt lgkmcnt(0)
	v_add_f32_e32 v60, v60, v61
	ds_bpermute_b32 v61, v62, v60
	v_cndmask_b32_e32 v62, v32, v37, vcc
	v_lshlrev_b32_e32 v62, 2, v62
	v_cmp_lt_i32_e32 vcc, v38, v33
	s_waitcnt lgkmcnt(0)
	v_add_f32_e32 v60, v60, v61
	ds_bpermute_b32 v61, v62, v60
	v_cndmask_b32_e32 v62, v32, v38, vcc
	v_lshlrev_b32_e32 v62, 2, v62
	v_cmp_lt_i32_e32 vcc, v39, v33
	s_waitcnt lgkmcnt(0)
	v_add_f32_e32 v60, v60, v61
	ds_bpermute_b32 v61, v62, v60
	v_cndmask_b32_e32 v62, v32, v39, vcc
	v_lshlrev_b32_e32 v62, 2, v62
	s_waitcnt lgkmcnt(0)
	v_add_f32_e32 v60, v60, v61
	ds_bpermute_b32 v61, v62, v60
	s_waitcnt lgkmcnt(0)
	v_add_f32_e32 v60, v60, v61
	v_fmamk_f32 v60, v60, 0x3a000000, v30
	v_mul_f32_e32 v61, 0x4f800000, v60
	v_cmp_gt_f32_e32 vcc, s5, v60
	s_nop 1
	v_cndmask_b32_e32 v60, v60, v61, vcc
	v_sqrt_f32_e32 v61, v60
	s_nop 0
	v_add_u32_e32 v62, -1, v61
	v_add_u32_e32 v63, 1, v61
	v_fma_f32 v64, -v62, v61, v60
	v_fma_f32 v65, -v63, v61, v60
	v_cmp_ge_f32_e64 s[0:1], 0, v64
	s_nop 1
	v_cndmask_b32_e64 v61, v61, v62, s[0:1]
	v_cmp_lt_f32_e64 s[0:1], 0, v65
	s_nop 1
	v_cndmask_b32_e64 v61, v61, v63, s[0:1]
	v_mul_f32_e32 v62, 0x37800000, v61
	v_cndmask_b32_e32 v61, v61, v62, vcc
	v_cmp_class_f32_e32 vcc, v60, v31
	s_nop 1
	v_cndmask_b32_e32 v60, v61, v60, vcc
	v_div_scale_f32 v61, s[0:1], v60, v60, 1.0
	v_rcp_f32_e32 v62, v61
	v_div_scale_f32 v63, vcc, 1.0, v60, 1.0
	v_fma_f32 v64, -v61, v62, 1.0
	v_fmac_f32_e32 v62, v64, v62
	v_mul_f32_e32 v64, v63, v62
	v_fma_f32 v65, -v61, v64, v63
	v_fmac_f32_e32 v64, v65, v62
	v_fma_f32 v61, -v61, v64, v63
	v_div_fmas_f32 v61, v61, v62, v64
	v_div_fixup_f32 v60, v61, v60, 1.0
	s_waitcnt vmcnt(0)
	v_pk_mul_f32 v[40:41], v[60:61], v[40:41] op_sel_hi:[0,1]
	v_pk_mul_f32 v[42:43], v[60:61], v[42:43] op_sel_hi:[0,1]
	v_pk_mul_f32 v[40:41], v[96:97], v[40:41]
	v_pk_mul_f32 v[42:43], v[98:99], v[42:43]
	global_store_dwordx4 v16, v[40:43], s[8:9]
	v_pk_mul_f32 v[44:45], v[60:61], v[44:45] op_sel_hi:[0,1]
	v_pk_mul_f32 v[46:47], v[60:61], v[46:47] op_sel_hi:[0,1]
	v_pk_mul_f32 v[44:45], v[100:101], v[44:45]
	v_pk_mul_f32 v[46:47], v[102:103], v[46:47]
	global_store_dwordx4 v16, v[44:47], s[8:9] offset:1024
	v_pk_mul_f32 v[48:49], v[60:61], v[48:49] op_sel_hi:[0,1]
	v_pk_mul_f32 v[50:51], v[60:61], v[50:51] op_sel_hi:[0,1]
	v_pk_mul_f32 v[48:49], v[104:105], v[48:49]
	v_pk_mul_f32 v[50:51], v[106:107], v[50:51]
	global_store_dwordx4 v16, v[48:51], s[8:9] offset:2048
	v_pk_mul_f32 v[52:53], v[60:61], v[52:53] op_sel_hi:[0,1]
	v_pk_mul_f32 v[54:55], v[60:61], v[54:55] op_sel_hi:[0,1]
	v_pk_mul_f32 v[52:53], v[108:109], v[52:53]
	v_pk_mul_f32 v[54:55], v[110:111], v[54:55]
	global_store_dwordx4 v16, v[52:55], s[8:9] offset:3072
	v_lshl_add_u64 v[56:57], s[8:9], 0, v[16:17]
	v_add_co_u32_e32 v56, vcc, s15, v56
	s_nop 1
	v_addc_co_u32_e32 v57, vcc, 0, v57, vcc
	v_pk_mul_f32 v[0:1], v[60:61], v[0:1] op_sel_hi:[0,1]
	v_pk_mul_f32 v[2:3], v[60:61], v[2:3] op_sel_hi:[0,1]
	v_pk_mul_f32 v[0:1], v[112:113], v[0:1]
	v_pk_mul_f32 v[2:3], v[114:115], v[2:3]
	global_store_dwordx4 v[56:57], v[0:3], off
	v_pk_mul_f32 v[8:9], v[60:61], v[8:9] op_sel_hi:[0,1]
	v_pk_mul_f32 v[10:11], v[60:61], v[10:11] op_sel_hi:[0,1]
	v_pk_mul_f32 v[8:9], v[116:117], v[8:9]
	v_pk_mul_f32 v[10:11], v[118:119], v[10:11]
	global_store_dwordx4 v[56:57], v[8:11], off offset:1024
	v_pk_mul_f32 v[12:13], v[60:61], v[12:13] op_sel_hi:[0,1]
	v_pk_mul_f32 v[14:15], v[60:61], v[14:15] op_sel_hi:[0,1]
	v_pk_mul_f32 v[12:13], v[120:121], v[12:13]
	v_pk_mul_f32 v[14:15], v[122:123], v[14:15]
	global_store_dwordx4 v[56:57], v[12:15], off offset:2048
	v_pk_mul_f32 v[4:5], v[60:61], v[4:5] op_sel_hi:[0,1]
	v_pk_mul_f32 v[6:7], v[60:61], v[6:7] op_sel_hi:[0,1]
	v_pk_mul_f32 v[4:5], v[124:125], v[4:5]
	v_pk_mul_f32 v[6:7], v[126:127], v[6:7]
	global_store_dwordx4 v[56:57], v[4:7], off offset:3072
	s_branch .LBB0_1601
